# k23 plus non-temporal hint on single-use attention Q loads
# baseline (speedup 1.0000x reference)
; #define lane lane_id()
; template <bool ROPE, bool ALIBI, int QP, int Q2P, int KP, int VP, int OP>
; __device__ __forceinline__ void attn_unit(const Unit& u, char* lds, const int wid) {
;     ...
;     bf16x8 qr[8]; const char* q2l = lds + OFF_Q2 + wid * 4096 + lane * 16;
; #pragma unroll
;     for (int d0 = 0; d0 < 8; ++d0) { const bf16x8 qv = *(const bf16x8*)(u.Q + (size_t)(wid * QBLK + r32) * QP + d0 * 16 + hi * 8);
;         if (ALIBI && d0 >= 6) *(bf16x8*)(lds + OFF_Q2 + wid * 4096 + lane * 16 + (d0 - 6) * 1024) = qv; else qr[d0] = qv; }
;     if constexpr (ROPE) {
; #pragma unroll
;         for (int e = 0; e < 4; ++e) *(bf16x8*)(lds + OFF_Q2 + wid * 4096 + lane * 16 + e * 1024) = *(const bf16x8*)(u.Q2 + (size_t)(wid * QBLK + r32) * Q2P + e * 16 + hi * 8);
; __global__ void __launch_bounds__(NWAVES * 64, 2) hybrid_fwd(Args args) {
;     ...
;             } else { const int qb = code & 15, h = (code >> 4) & 15, b = (code >> 8) & 3;
;                 const size_t qrow = (size_t)b * SEQ + (size_t)qb * 256, mrow = (size_t)MR + 64 * b, hk = (size_t)(2 * h) * MP, hv = (size_t)(2 * h + 1) * MP;
;                 u.Q = QN + ((size_t)h * MR + qrow) * 128; u.Q2 = QR + ((size_t)h * MR + qrow) * 64;
.LBB0_693:
	s_and_b32 s9, s71, 15
	s_bfe_u32 s4, s71, 0x20008
	s_bfe_u32 s88, s71, 0x40004
	s_lshl_b32 s17, s4, 12
	s_lshl_b32 s5, s9, 8
	s_or_b32 s89, s17, s5
	s_lshl_b32 s5, s88, 14
	s_mul_i32 s6, s88, 0x8200
	s_or_b32 s5, s89, s5
	s_add_i32 s16, s6, 0x4100
	s_lshl_b32 s7, s5, 8
	v_readlane_b32 s35, v254, 5
	s_add_u32 s52, s35, s7
	v_readlane_b32 s7, v254, 25
	v_mbcnt_lo_u32_b32 v75, -1, 0
	v_mbcnt_hi_u32_b32 v75, -1, v75
	v_readlane_b32 s56, v254, 10
	v_and_b32_e32 v74, 31, v75
	v_ashrrev_i32_e32 v18, 5, v75
	s_addc_u32 s53, s7, 0
	s_lshl_b32 s5, s5, 7
	v_or_b32_e32 v20, s56, v74
	v_mov_b32_e32 v21, v2
	v_lshlrev_b32_e32 v6, 3, v18
	s_add_u32 s54, s38, s5
	v_lshlrev_b64 v[4:5], 8, v[20:21]
	v_ashrrev_i32_e32 v7, 31, v6
	s_addc_u32 s55, s39, 0
	v_lshl_add_u64 v[4:5], s[52:53], 0, v[4:5]
	v_lshlrev_b64 v[22:23], 1, v[6:7]
	v_lshlrev_b64 v[20:21], 7, v[20:21]
	v_lshl_add_u64 v[24:25], v[4:5], 0, v[22:23]
	v_lshl_add_u64 v[20:21], s[54:55], 0, v[20:21]
	global_load_dwordx4 v[4:7], v[24:25], off nt
	global_load_dwordx4 v[8:11], v[24:25], off offset:32 nt
	global_load_dwordx4 v[12:15], v[24:25], off offset:64 nt
	global_load_dwordx4 v[114:117], v[24:25], off offset:96 nt
	global_load_dwordx4 v[118:121], v[24:25], off offset:128 nt
	global_load_dwordx4 v[122:125], v[24:25], off offset:160 nt
	global_load_dwordx4 v[126:129], v[24:25], off offset:192 nt
	global_load_dwordx4 v[130:133], v[24:25], off offset:224 nt
	v_lshl_add_u64 v[24:25], v[20:21], 0, v[22:23]
	global_load_dwordx4 v[44:47], v[24:25], off nt
	global_load_dwordx4 v[48:51], v[24:25], off offset:32 nt
	global_load_dwordx4 v[52:55], v[24:25], off offset:64 nt
	global_load_dwordx4 v[56:59], v[24:25], off offset:96 nt
	v_lshlrev_b32_e32 v0, 4, v75
	v_add_u32_e32 v17, s82, v0
	s_and_b64 vcc, exec, s[2:3]
	v_readlane_b32 s57, v254, 11
	s_cbranch_vccnz .LBB0_695
	s_setprio 1

; __device__ __forceinline__ int v_st(int k, int c) { const int kk = (k & ~0xC) | ((k & 4) << 1) | ((k & 8) >> 1); return ((kk >> 3) * 4 + (c >> 5)) * 512 + ((kk & 7) * 32 + (c & 31)) * 2; }
; #define lane lane_id()
; template <int OP>
; __device__ __forceinline__ void attn_unit_x(const UnitX& u, char* lds, const int wid) {
;     ...
;     { const float* qs = u.qst + (2 * u.qb) * 2;
;       const float qn2 = fmaxf(qs[0], qs[2]), mlb = fminf(qs[1], qs[3]);
;       const int t = lane + 1, dmin = 128 * u.qb - 64 * t + 1;
;       const bool inr = t < 2 * u.qb + 3 && dmin > 0;
;       const float kn2v = inr ? u.kn2[t] : 0.f;
;       float k1_ = 1.001f, k2_ = 104.51f; asm volatile("" : "+v"(k1_), "+v"(k2_));
;       const float ub = sqrtf(qn2 * kn2v) * k1_ + u.nslope * (float)dmin;
;       const unsigned long long bal = __ballot(inr && ub < mlb - k2_);
;       const int t_lo = 1 + __builtin_ctzll(~bal);
;       toff = __builtin_amdgcn_readfirstlane((t_lo - 1) & ~1); }
;     const int NT = 2 * u.qb + 3 - toff;
;     const int jq = 1 + 2 * u.qb + (g >> 1);
;     char* K_lds = lds + XOFF_K; char* Vh_lds = lds + XOFF_V + vh * 32768;
;     char* pbuf = lds + XOFF_P + g * 8192 + lane * 16;
;     float* psc = (float*)(lds + XOFF_PS) + g * 128;
;     float l_reg = 0.f; f32x16 o[4] = {};
;     const int sr = tid >> 4, sc = (tid & 15) * 8, vst0 = v_st(sr, sc), vst1 = v_st(32 + sr, sc), kws = KSWZ(sr, sc * 2);
;     const int vb0 = (int)(uintptr_t)Vh_lds + v_rd_base(lane);
;     const unsigned so0 = (unsigned)(sr * 128 + sc) * 2u, so1 = (unsigned)((32 + sr) * 128 + sc) * 2u;
;     bf16x8 st_k0, st_k1, st_a0, st_a1, st_b0, st_b1;
;     bf16x8 qr[8];
; #pragma unroll
;     for (int d0 = 0; d0 < 8; ++d0) qr[d0] = *(const bf16x8*)(u.Q + (size_t)(g * QBLK + r32) * 128 + d0 * 16 + hi * 8);
;     unsigned qw0s, qw1s; float n2s;
;     { const float sl = -u.nslope;
;       qw0s = (unsigned)__builtin_amdgcn_readfirstlane((int)((__float_as_uint(64.f * sl) >> 16) | (__float_as_uint(sl) & 0xffff0000u)));
;       qw1s = (unsigned)__builtin_amdgcn_readfirstlane((int)(__float_as_uint(16.f * sl) >> 16)); n2s = -2.f * sl; }
;     ...
;     { XLOAD_K(1); const bf16x8 n0_ = st_k0, n1_ = st_k1;
;       XLOAD_K(0); XLOAD_V(0); XVMW(); XWRITE_K(0); XWRITE_V(0);
;       *(bf16x8*)(K_lds + SHM_K + kws) = n0_; *(bf16x8*)(K_lds + SHM_K + kws + 32 * 256) = n1_; }
;     __syncthreads();
.LBB0_715:
	s_or_b64 exec, exec, s[4:5]
	s_or_b32 s61, s9, s6
	s_add_i32 s4, s7, s61
	s_lshl_b32 s4, s4, 8
	s_add_u32 s56, s14, s4
	s_addc_u32 s57, s15, 0
	s_add_i32 s4, s7, s9
	s_lshl_b32 s4, s4, 8
	s_add_u32 s63, s74, s4
	s_addc_u32 s64, s75, 0
	s_add_i32 s7, s7, s40
	s_lshl_b32 s4, s7, 8
	s_add_u32 s54, s74, s4
	s_addc_u32 s55, s75, 0
	s_add_i32 s4, s40, s35
	s_lshl_b32 s4, s4, 8
	s_add_u32 s6, s76, s4
	s_addc_u32 s7, s77, 0
	s_add_i32 s4, s17, s40
	s_lshl_b32 s4, s4, 8
	s_add_u32 s52, s76, s4
	s_addc_u32 s53, s77, 0
	s_add_i32 s4, s42, 1
	v_cvt_f32_ubyte0_e32 v3, s4
	s_mov_b32 s4, 0x42fc0000
	v_cmp_lt_f32_e32 vcc, s4, v3
	s_and_b64 s[4:5], vcc, exec
	s_waitcnt vmcnt(0)
	v_max_f32_e32 v6, v6, v6
	v_cndmask_b32_e32 v8, 0, v220, vcc
	v_sub_f32_e32 v3, v8, v3
	v_exp_f32_e32 v3, v3
	v_max_f32_e32 v4, v4, v4
	s_cselect_b32 s4, 0xffffffc0, 0
	v_max_f32_e32 v4, v4, v6
	v_ldexp_f32 v19, v3, s4
	v_mul_f32_e32 v1, v4, v1
	s_mov_b32 s4, 0xf800000
	v_cmp_gt_f32_e32 vcc, s4, v1
	v_mul_f32_e32 v4, 0x4f800000, v1
	v_max_f32_e32 v6, v7, v7
	v_cndmask_b32_e32 v1, v1, v4, vcc
	v_sqrt_f32_e32 v4, v1
	v_max_f32_e32 v5, v5, v5
	v_min_f32_e32 v5, v5, v6
	v_or_b32_e32 v6, 1, v0
	v_add_u32_e32 v8, -1, v4
	v_fma_f32 v9, -v8, v4, v1
	v_cmp_ge_f32_e64 s[4:5], 0, v9
	v_add_u32_e32 v9, 1, v4
	v_mov_b32_e32 v7, 0x42d1051f
	v_cndmask_b32_e64 v8, v4, v8, s[4:5]
	v_fma_f32 v4, -v9, v4, v1
	v_cmp_lt_f32_e64 s[4:5], 0, v4
	v_mov_b32_e32 v0, 0x3f8020c5
	v_add_u32_e32 v3, s11, v210
	v_cndmask_b32_e64 v4, v8, v9, s[4:5]
	v_mul_f32_e32 v8, 0x37800000, v4
	v_cndmask_b32_e32 v4, v4, v8, vcc
	v_cmp_class_f32_e32 vcc, v1, v218
	v_lshlrev_b32_e32 v17, 3, v210
	v_and_b32_e32 v211, 31, v210
	v_cndmask_b32_e32 v18, v4, v1, vcc
	v_cvt_f32_i32_e32 v1, v6
	v_ashrrev_i32_e32 v209, 5, v210
	v_readlane_b32 s1, v254, 36
	v_lshlrev_b32_e32 v232, 4, v209
	v_pk_mul_f32 v[0:1], v[18:19], v[0:1]
	s_nop 0
	v_mov_b32_e32 v4, v0
	v_mov_b32_e32 v6, v1
	v_pk_add_f32 v[0:1], v[4:5], v[6:7] neg_lo:[0,1] neg_hi:[0,1]
	v_ashrrev_i32_e32 v6, 4, v3
	v_cmp_lt_f32_e32 vcc, v0, v1
	v_and_b32_e32 v1, 0xfffff0, v6
	v_lshlrev_b32_e32 v4, 1, v6
	v_and_or_b32 v1, v4, 8, v1
	v_lshrrev_b32_e32 v1, 1, v1
	v_bfe_u32 v5, v17, 5, 2
	s_and_b64 s[4:5], s[58:59], vcc
	v_or_b32_e32 v1, v1, v5
	v_cndmask_b32_e64 v0, 0, 1, s[4:5]
	v_lshrrev_b32_e32 v4, 1, v6
	v_lshlrev_b32_e32 v7, 9, v1
	v_and_b32_e32 v1, 3, v6
	v_cmp_ne_u32_e32 vcc, 0, v0
	v_and_b32_e32 v0, 0x78, v17
	v_and_or_b32 v1, v4, 4, v1
	v_add_u32_e32 v11, 32, v6
	v_lshlrev_b32_e32 v8, 6, v1
	v_lshlrev_b32_e32 v9, 1, v0
	v_and_b32_e32 v0, 0xfffff0, v11
	v_lshlrev_b32_e32 v1, 1, v11
	v_and_or_b32 v0, v1, 8, v0
	v_lshrrev_b32_e32 v0, 1, v0
	v_or_b32_e32 v0, v0, v5
	v_and_b32_e32 v10, 48, v9
	v_lshlrev_b32_e32 v0, 9, v0
	v_or3_b32 v18, v0, v8, v10
	v_lshl_or_b32 v0, v211, 8, s1
	v_mov_b32_e32 v1, v2
	v_lshlrev_b32_e32 v4, 3, v209
	v_lshl_add_u64 v[0:1], s[56:57], 0, v[0:1]
	v_ashrrev_i32_e32 v5, 31, v4
	v_lshl_add_u64 v[0:1], v[4:5], 1, v[0:1]
	v_and_b32_e32 v3, 0x70, v3
	global_load_dwordx4 v[160:163], v[0:1], off nt
	global_load_dwordx4 v[164:167], v[0:1], off offset:32 nt
	global_load_dwordx4 v[168:171], v[0:1], off offset:64 nt
	global_load_dwordx4 v[172:175], v[0:1], off offset:96 nt
	global_load_dwordx4 v[176:179], v[0:1], off offset:128 nt
	global_load_dwordx4 v[180:183], v[0:1], off offset:160 nt
	global_load_dwordx4 v[184:187], v[0:1], off offset:192 nt
	global_load_dwordx4 v[188:191], v[0:1], off offset:224 nt
	v_lshlrev_b32_e32 v1, 8, v6
	v_bitop3_b32 v3, v9, v1, v3 bitop3:0xde
	v_or_b32_e32 v212, v1, v9
	v_mul_f32_e32 v1, 0x42800000, v19
	v_and_b32_e32 v4, 0x7fff0000, v19
	s_not_b64 s[4:5], vcc
	v_or_b32_sdwa v1, v1, v4 dst_sel:DWORD dst_unused:UNUSED_PAD src0_sel:WORD_1 src1_sel:DWORD
	s_ff1_i32_b64 s40, s[4:5]
	v_readfirstlane_b32 s67, v1
	v_xor_b32_e32 v1, 0x80000000, v19
	s_and_b32 s66, s40, 62
	v_readfirstlane_b32 s4, v1
	v_or3_b32 v0, v7, v8, v10
	v_lshl_or_b32 v214, v11, 8, v9
	v_mul_f32_e32 v1, s4, v221
	s_lshl_b32 s4, s66, 14
	s_add_u32 s4, s63, s4
	s_addc_u32 s5, s64, 0
	global_load_dwordx4 v[4:7], v212, s[4:5]
	global_load_dwordx4 v[8:11], v214, s[4:5]
	global_load_dwordx4 v[192:195], v212, s[54:55]
	global_load_dwordx4 v[196:199], v214, s[54:55]
	global_load_dwordx4 v[12:15], v212, s[6:7]
	global_load_dwordx4 v[20:23], v214, s[6:7]
	global_load_dwordx4 v[24:27], v212, s[52:53]
	global_load_dwordx4 v[28:31], v214, s[52:53]
	v_readlane_b32 s6, v254, 8
	v_lshrrev_b32_e32 v227, 16, v1
	v_add_u32_e32 v1, 0, v3
	v_readlane_b32 s7, v254, 9
	s_waitcnt vmcnt(0)
	v_add_u32_e32 v228, 0x10000, v1
	v_add_u32_e32 v229, 0, v0
	v_add_u32_e32 v230, 0, v18
	v_cndmask_b32_e64 v0, 0, 1, s[6:7]
	v_add_u32_e32 v231, 0x14000, v1
	v_cmp_ne_u32_e64 s[4:5], 1, v0
	v_cvt_f32_ubyte0_e32 v0, v211
	v_or_b32_e32 v1, 32, v211
	s_andn2_b64 vcc, exec, s[6:7]
	v_lshlrev_b32_e32 v18, 8, v211
	v_and_b32_e32 v233, 0x7fff0000, v0
	s_waitcnt vmcnt(5)
	ds_write_b128 v228, v[192:195]
	s_waitcnt vmcnt(4)
	ds_write_b128 v228, v[196:199] offset:8192
	s_waitcnt vmcnt(3)
	ds_write_b128 v229, v[12:15]
	s_waitcnt vmcnt(2)
	ds_write_b128 v230, v[20:23]
	s_waitcnt vmcnt(1)
	ds_write_b128 v229, v[24:27] offset:32768
	s_waitcnt vmcnt(0)
	ds_write_b128 v230, v[28:31] offset:32768
	v_lshlrev_b32_e32 v21, 4, v211
	v_cvt_f32_ubyte0_e32 v25, v1
	v_bitop3_b32 v20, v21, v232, s97 bitop3:0x6c
	v_add_u32_e32 v24, 32, v232
	v_add_u32_e32 v23, 64, v232
	v_add_u32_e32 v22, 0x60, v232
	ds_write_b128 v231, v[4:7]
	ds_write_b128 v231, v[8:11] offset:8192
	s_waitcnt lgkmcnt(0)
	s_barrier
; template <int KB, bool ROPE, bool AUG, bool QLDS = false>
; __device__ __forceinline__ void qkt(f32x16& p0, f32x16& p1, const char* K_lds, const char* K2_lds, int r32, int hi, const bf16x8* qr, const char* q2l, bf16x8 ka0, bf16x8 ka1, bf16x8 qa) {
;     p0 = f32x16{}; p1 = f32x16{};
;     const char* kb[4];
; #pragma unroll
;     for (int dd = 0; dd < 4; ++dd) kb[dd] = K_lds + KB * SHM_K + KSWZ(r32, (dd * 16 + hi * 8) * 2);
; #pragma unroll
;     for (int d0 = 0; d0 < 8; ++d0) { const char* a = kb[d0 & 3] + (d0 >> 2) * 128;
;         bf16x8 b0 = *reinterpret_cast<const bf16x8*>(a);
;         bf16x8 b1 = *reinterpret_cast<const bf16x8*>(a + 32 * 256);
;         bf16x8 qf; if (QLDS && d0 >= 6) qf = *reinterpret_cast<const bf16x8*>(q2l + (d0 - 6) * 1024); else qf = qr[d0];
;         p0 = __builtin_amdgcn_mfma_f32_32x32x16_bf16(b0, qf, p0, 0, 0, 0);
;         p1 = __builtin_amdgcn_mfma_f32_32x32x16_bf16(b1, qf, p1, 0, 0, 0); }
;     if constexpr (ROPE) {
; #pragma unroll
;         for (int e = 0; e < 4; ++e) { const char* a = K2_lds + KB * SHM_K2 + K2SWZ(r32, (e * 2 + hi) * 16);
;             bf16x8 b0 = *reinterpret_cast<const bf16x8*>(a);
;             bf16x8 b1 = *reinterpret_cast<const bf16x8*>(a + 32 * 128);
;             const bf16x8 q2 = *reinterpret_cast<const bf16x8*>(q2l + e * 1024);
;             p0 = __builtin_amdgcn_mfma_f32_32x32x16_bf16(b0, q2, p0, 0, 0, 0);
;             p1 = __builtin_amdgcn_mfma_f32_32x32x16_bf16(b1, q2, p1, 0, 0, 0); }
;     }
;     if constexpr (AUG) {
;         p0 = __builtin_amdgcn_mfma_f32_32x32x16_bf16(ka0, qa, p0, 0, 0, 0);
;         p1 = __builtin_amdgcn_mfma_f32_32x32x16_bf16(ka1, qa, p1, 0, 0, 0); }
	s_cbranch_vccnz .LBB0_717
	v_mov_b32_e32 v0, v209
	v_add3_u32 v1, s96, v20, v18
	ds_read_b128 v[4:7], v1
	v_bitop3_b32 v3, v24, v21, s97 bitop3:0x78
	v_add3_u32 v3, s96, v3, v18
	v_bitop3_b32 v8, v23, v21, s97 bitop3:0x78
	v_add3_u32 v8, s96, v8, v18
	v_bitop3_b32 v9, v22, v21, s97 bitop3:0x78
	v_add3_u32 v9, s96, v9, v18
	s_waitcnt lgkmcnt(0)
	v_mfma_f32_32x32x16_bf16 v[96:111], v[4:7], v[160:163], 0
	ds_read_b128 v[4:7], v1 offset:8192
	s_sub_i32 s6, 0, s16
	v_cmp_eq_u32_e32 vcc, 0, v0
	v_mov_b32_e32 v0, s67
	s_nop 0
	v_cndmask_b32_e32 v0, 0, v0, vcc
	s_waitcnt lgkmcnt(0)
	v_mfma_f32_32x32x16_bf16 v[112:127], v[4:7], v[160:163], 0
	ds_read_b128 v[4:7], v3
	s_waitcnt lgkmcnt(0)
	v_mfma_f32_32x32x16_bf16 v[96:111], v[4:7], v[164:167], v[96:111]
	ds_read_b128 v[4:7], v3 offset:8192
	s_waitcnt lgkmcnt(0)
	v_mfma_f32_32x32x16_bf16 v[112:127], v[4:7], v[164:167], v[112:127]
	ds_read_b128 v[4:7], v8
	s_waitcnt lgkmcnt(0)
	v_mfma_f32_32x32x16_bf16 v[96:111], v[4:7], v[168:171], v[96:111]
	ds_read_b128 v[4:7], v8 offset:8192
	s_waitcnt lgkmcnt(0)
	v_mfma_f32_32x32x16_bf16 v[112:127], v[4:7], v[168:171], v[112:127]
	ds_read_b128 v[4:7], v9
	s_waitcnt lgkmcnt(0)
	v_mfma_f32_32x32x16_bf16 v[96:111], v[4:7], v[172:175], v[96:111]
	ds_read_b128 v[4:7], v9 offset:8192
	s_waitcnt lgkmcnt(0)
	v_mfma_f32_32x32x16_bf16 v[112:127], v[4:7], v[172:175], v[112:127]
	ds_read_b128 v[4:7], v1 offset:128
	s_waitcnt lgkmcnt(0)
	v_mfma_f32_32x32x16_bf16 v[96:111], v[4:7], v[176:179], v[96:111]
	ds_read_b128 v[4:7], v1 offset:8320
	v_cndmask_b32_e32 v1, 0, v227, vcc
	s_waitcnt lgkmcnt(0)
	v_mfma_f32_32x32x16_bf16 v[112:127], v[4:7], v[176:179], v[112:127]
	ds_read_b128 v[4:7], v3 offset:128
	s_waitcnt lgkmcnt(0)
	v_mfma_f32_32x32x16_bf16 v[96:111], v[4:7], v[180:183], v[96:111]
	ds_read_b128 v[4:7], v3 offset:8320
	v_cvt_f32_i32_e32 v3, s6
	v_lshrrev_b32_e32 v3, 16, v3
	v_cndmask_b32_e32 v12, 0, v3, vcc
	s_waitcnt lgkmcnt(0)
	v_mfma_f32_32x32x16_bf16 v[112:127], v[4:7], v[180:183], v[112:127]
	ds_read_b128 v[4:7], v8 offset:128
	v_cndmask_b32_e32 v3, 0, v233, vcc
	s_waitcnt lgkmcnt(0)
	v_mfma_f32_32x32x16_bf16 v[96:111], v[4:7], v[184:187], v[96:111]
	ds_read_b128 v[4:7], v8 offset:8320
	s_waitcnt lgkmcnt(0)
	v_mfma_f32_32x32x16_bf16 v[112:127], v[4:7], v[184:187], v[112:127]
	ds_read_b128 v[4:7], v9 offset:128
	ds_read_b128 v[8:11], v9 offset:8320
	s_waitcnt lgkmcnt(1)
	v_mfma_f32_32x32x16_bf16 v[96:111], v[4:7], v[188:191], v[96:111]
	v_cndmask_b32_e32 v5, 0, v222, vcc
	v_or_b32_e32 v4, v12, v3
	v_mov_b32_e32 v6, v2
	v_mov_b32_e32 v7, v2
	v_mov_b32_e32 v3, v2
	s_waitcnt lgkmcnt(0)
	v_mfma_f32_32x32x16_bf16 v[112:127], v[8:11], v[188:191], v[112:127]
	v_and_b32_e32 v8, 0x7fff0000, v25
	v_cndmask_b32_e32 v8, 0, v8, vcc
	v_or_b32_e32 v8, v12, v8
	v_mov_b32_e32 v9, v5
	v_mov_b32_e32 v10, v2
	v_mov_b32_e32 v11, v2
	v_mfma_f32_32x32x16_bf16 v[96:111], v[4:7], v[0:3], v[96:111]
	s_nop 0
	v_mfma_f32_32x32x16_bf16 v[112:127], v[8:11], v[0:3], v[112:127]
	s_branch .LBB0_718
